# combo18 + W_o ctx split-K units' f32 epilogue de-serialised: the 8 per-row sum-of-squares fetches issued together (was fetch -> vmcnt(0) -> scale -> 4 stores, eight times; each wait also drained the p
# speedup vs baseline: 1.0157x; 1.0059x over previous
;     __device__ __forceinline__ void operator()(const f32x4 (&acc)[2][2][4][2], const Unit& u, int wr, int wc, int fr, int fq) const {
;     ...
;         if (u.nt != ntfull) {
;             const int seg = (u.kt0 == 0) ? 0 : (u.kt0 == 6 ? 1 : 2); const float nn = (seg == 1) ? (1.0f / 256.0f) : (1.0f / 384.0f);
;             const int crow0 = (u.pm == 32 ? 0 : 256) + wr * 64 + fr; const int slice = SEG ? seg : (u.kt0 >> 2);
; #pragma unroll
;             for (int ai = 0; ai < 2; ++ai)
; #pragma unroll
;                 for (int m = 0; m < 4; ++m) { const int row = row0 + ai * HALF + m * 16; float* yp = y32 + ((size_t)slice * 512 + crow0 + ai * HALF + m * 16) * DM + col0;
;                     float sc = 1.0f; if (SEG) sc = 1.0f / sqrtf(ss[(size_t)row * 4 + seg] * nn + LN_EPS);
; #pragma unroll
;                     for (int bj = 0; bj < 2; ++bj)
; #pragma unroll
;                         for (int n = 0; n < 2; ++n) *(f32x4*)(yp + bj * HALF + 4 * n) = acc[ai][bj][m][n] * sc; }
.LBB0_491:
	v_lshl_or_b32 v0, s2, 8, v167
	v_or_b32_e32 v150, s39, v0
	s_mov_b64 s[0:1], -1
	s_and_b64 vcc, exec, s[22:23]
	v_or_b32_e32 v136, 16, v144
	v_or_b32_e32 v134, 32, v144
	v_or_b32_e32 v2, 48, v144
	s_cbranch_vccz .LBB0_493
	s_add_u32 s14, s16, 0x15040000
	s_addc_u32 s15, s17, 0
	s_cmp_eq_u32 s36, 6
	s_cselect_b64 vcc, -1, 0
	s_and_b64 s[0:1], vcc, exec
	s_cselect_b32 s0, 1, 2
	s_cmp_eq_u32 s12, 32
	s_cselect_b32 s1, 0, 0x100
	s_cmp_lg_u32 s36, 0
	v_add_u32_e32 v138, s1, v17
	v_ashrrev_i32_e32 v139, 31, v138
	s_cselect_b32 s0, s0, 0
	s_lshl_b32 s86, s0, 21
	v_lshlrev_b64 v[138:139], 12, v[138:139]
	v_lshl_add_u64 v[142:143], v[138:139], 0, s[86:87]
	s_lshl_b32 s86, s0, 2
	v_lshl_add_u64 v[140:141], v[146:147], 0, s[86:87]
	flat_load_dword v242, v[140:141]
	flat_load_dword v243, v[140:141] offset:256
	flat_load_dword v244, v[140:141] offset:512
	flat_load_dword v245, v[140:141] offset:768
	flat_load_dword v246, v[140:141] offset:2048
	flat_load_dword v247, v[140:141] offset:2304
	flat_load_dword v248, v[140:141] offset:2560
	flat_load_dword v249, v[140:141] offset:2816
	v_cndmask_b32_e32 v151, v221, v222, vcc
	v_lshl_add_u64 v[138:139], s[14:15], 0, v[142:143]
	v_lshlrev_b32_e32 v0, 2, v150
	v_lshl_add_u64 v[138:139], v[138:139], 0, v[0:1]
	s_waitcnt vmcnt(0) lgkmcnt(0)
	v_mov_b32_e32 v3, v242
	v_fmaak_f32 v3, v151, v3, 0x358637bd
	v_cmp_gt_f32_e32 vcc, s69, v3
	v_mul_f32_e32 v135, 0x4f800000, v3
	s_nop 0
	v_cndmask_b32_e32 v3, v3, v135, vcc
	v_sqrt_f32_e32 v135, v3
	s_nop 0
	v_add_u32_e32 v137, -1, v135
	v_fma_f32 v148, -v137, v135, v3
	v_cmp_ge_f32_e64 s[0:1], 0, v148
	v_add_u32_e32 v148, 1, v135
	s_nop 0
	v_cndmask_b32_e64 v137, v135, v137, s[0:1]
	v_fma_f32 v135, -v148, v135, v3
	v_cmp_lt_f32_e64 s[0:1], 0, v135
	s_nop 1
	v_cndmask_b32_e64 v135, v137, v148, s[0:1]
	v_mul_f32_e32 v137, 0x37800000, v135
	v_cndmask_b32_e32 v135, v135, v137, vcc
	v_cmp_class_f32_e32 vcc, v3, v217
	s_nop 1
	v_cndmask_b32_e32 v3, v135, v3, vcc
	v_div_scale_f32 v135, s[0:1], v3, v3, 1.0
	v_rcp_f32_e32 v137, v135
	s_nop 0
	v_fma_f32 v148, -v135, v137, 1.0
	v_fmac_f32_e32 v137, v148, v137
	v_div_scale_f32 v148, vcc, 1.0, v3, 1.0
	v_mul_f32_e32 v149, v148, v137
	v_fma_f32 v152, -v135, v149, v148
	v_fmac_f32_e32 v149, v152, v137
	v_fma_f32 v135, -v135, v149, v148
	v_div_fmas_f32 v135, v135, v137, v149
	v_div_fixup_f32 v148, v135, v3, 1.0
	v_pk_mul_f32 v[154:155], v[132:133], v[148:149] op_sel_hi:[1,0]
	v_pk_mul_f32 v[152:153], v[130:131], v[148:149] op_sel_hi:[1,0]
	flat_store_dwordx4 v[138:139], v[152:155]
	v_ashrrev_i32_e32 v137, 31, v136
	s_nop 0
	v_pk_mul_f32 v[154:155], v[128:129], v[148:149] op_sel_hi:[1,0]
	v_pk_mul_f32 v[152:153], v[126:127], v[148:149] op_sel_hi:[1,0]
	flat_store_dwordx4 v[138:139], v[152:155] offset:16
	s_nop 1
	v_pk_mul_f32 v[154:155], v[124:125], v[148:149] op_sel_hi:[1,0]
	v_pk_mul_f32 v[152:153], v[122:123], v[148:149] op_sel_hi:[1,0]
	flat_store_dwordx4 v[138:139], v[152:155] offset:512
	s_nop 1
	v_pk_mul_f32 v[154:155], v[120:121], v[148:149] op_sel_hi:[1,0]
	v_pk_mul_f32 v[152:153], v[118:119], v[148:149] op_sel_hi:[1,0]
	flat_store_dwordx4 v[138:139], v[152:155] offset:528
	v_or_b32_e32 v148, 0x10000, v142
	v_mov_b32_e32 v149, v143
	v_lshl_add_u64 v[152:153], v[136:137], 4, s[8:9]
	v_lshl_add_u64 v[152:153], v[152:153], 0, s[86:87]
	v_mov_b32_e32 v3, v243
	v_lshl_add_u64 v[148:149], s[14:15], 0, v[148:149]
	v_lshl_add_u64 v[148:149], v[148:149], 0, v[0:1]
	v_fmaak_f32 v3, v151, v3, 0x358637bd
	v_cmp_gt_f32_e32 vcc, s69, v3
	v_mul_f32_e32 v135, 0x4f800000, v3
	s_nop 0
	v_cndmask_b32_e32 v3, v3, v135, vcc
	v_sqrt_f32_e32 v135, v3
	s_nop 0
	v_add_u32_e32 v137, -1, v135
	v_fma_f32 v152, -v137, v135, v3
	v_cmp_ge_f32_e64 s[0:1], 0, v152
	v_add_u32_e32 v152, 1, v135
	s_nop 0
	v_cndmask_b32_e64 v137, v135, v137, s[0:1]
	v_fma_f32 v135, -v152, v135, v3
	v_cmp_lt_f32_e64 s[0:1], 0, v135
	s_nop 1
	v_cndmask_b32_e64 v135, v137, v152, s[0:1]
	v_mul_f32_e32 v137, 0x37800000, v135
	v_cndmask_b32_e32 v135, v135, v137, vcc
	v_cmp_class_f32_e32 vcc, v3, v217
	s_nop 1
	v_cndmask_b32_e32 v3, v135, v3, vcc
	v_div_scale_f32 v135, s[0:1], v3, v3, 1.0
	v_rcp_f32_e32 v137, v135
	s_nop 0
	v_fma_f32 v152, -v135, v137, 1.0
	v_fmac_f32_e32 v137, v152, v137
	v_div_scale_f32 v152, vcc, 1.0, v3, 1.0
	v_mul_f32_e32 v153, v152, v137
	v_fma_f32 v154, -v135, v153, v152
	v_fmac_f32_e32 v153, v154, v137
	v_fma_f32 v135, -v135, v153, v152
	v_div_fmas_f32 v135, v135, v137, v153
	v_div_fixup_f32 v156, v135, v3, 1.0
	v_pk_mul_f32 v[154:155], v[116:117], v[156:157] op_sel_hi:[1,0]
	v_pk_mul_f32 v[152:153], v[114:115], v[156:157] op_sel_hi:[1,0]
	flat_store_dwordx4 v[148:149], v[152:155]
	v_ashrrev_i32_e32 v135, 31, v134
	s_nop 0
	v_pk_mul_f32 v[154:155], v[112:113], v[156:157] op_sel_hi:[1,0]
	v_pk_mul_f32 v[152:153], v[110:111], v[156:157] op_sel_hi:[1,0]
	flat_store_dwordx4 v[148:149], v[152:155] offset:16
	s_nop 1
	v_pk_mul_f32 v[154:155], v[108:109], v[156:157] op_sel_hi:[1,0]
	v_pk_mul_f32 v[152:153], v[106:107], v[156:157] op_sel_hi:[1,0]
	flat_store_dwordx4 v[148:149], v[152:155] offset:512
	s_nop 1
	v_pk_mul_f32 v[154:155], v[104:105], v[156:157] op_sel_hi:[1,0]
	v_pk_mul_f32 v[152:153], v[102:103], v[156:157] op_sel_hi:[1,0]
	flat_store_dwordx4 v[148:149], v[152:155] offset:528
	v_or_b32_e32 v148, 0x20000, v142
	v_mov_b32_e32 v149, v143
	v_lshl_add_u64 v[152:153], v[134:135], 4, s[8:9]
	v_lshl_add_u64 v[152:153], v[152:153], 0, s[86:87]
	v_mov_b32_e32 v3, v244
	v_lshl_add_u64 v[148:149], s[14:15], 0, v[148:149]
	v_lshl_add_u64 v[148:149], v[148:149], 0, v[0:1]
	v_or_b32_e32 v142, 0x30000, v142
	v_lshl_add_u64 v[142:143], s[14:15], 0, v[142:143]
;     __device__ __forceinline__ void operator()(const f32x4 (&acc)[2][2][4][2], const Unit& u, int wr, int wc, int fr, int fq) const {
;     ...
;                 for (int m = 0; m < 4; ++m) { const int row = row0 + ai * HALF + m * 16; float* yp = y32 + ((size_t)slice * 512 + crow0 + ai * HALF + m * 16) * DM + col0;
;                     float sc = 1.0f; if (SEG) sc = 1.0f / sqrtf(ss[(size_t)row * 4 + seg] * nn + LN_EPS);
; #pragma unroll
;                     for (int bj = 0; bj < 2; ++bj)
; #pragma unroll
;                         for (int n = 0; n < 2; ++n) *(f32x4*)(yp + bj * HALF + 4 * n) = acc[ai][bj][m][n] * sc; }
	v_lshl_add_u64 v[142:143], v[142:143], 0, v[0:1]
	v_fmaak_f32 v3, v151, v3, 0x358637bd
	v_cmp_gt_f32_e32 vcc, s69, v3
	v_mul_f32_e32 v135, 0x4f800000, v3
	s_nop 0
	v_cndmask_b32_e32 v3, v3, v135, vcc
	v_sqrt_f32_e32 v135, v3
	s_nop 0
	v_add_u32_e32 v137, -1, v135
	v_fma_f32 v152, -v137, v135, v3
	v_cmp_ge_f32_e64 s[0:1], 0, v152
	v_add_u32_e32 v152, 1, v135
	s_nop 0
	v_cndmask_b32_e64 v137, v135, v137, s[0:1]
	v_fma_f32 v135, -v152, v135, v3
	v_cmp_lt_f32_e64 s[0:1], 0, v135
	s_nop 1
	v_cndmask_b32_e64 v135, v137, v152, s[0:1]
	v_mul_f32_e32 v137, 0x37800000, v135
	v_cndmask_b32_e32 v135, v135, v137, vcc
	v_cmp_class_f32_e32 vcc, v3, v217
	s_nop 1
	v_cndmask_b32_e32 v3, v135, v3, vcc
	v_div_scale_f32 v135, s[0:1], v3, v3, 1.0
	v_rcp_f32_e32 v137, v135
	s_nop 0
	v_fma_f32 v152, -v135, v137, 1.0
	v_fmac_f32_e32 v137, v152, v137
	v_div_scale_f32 v152, vcc, 1.0, v3, 1.0
	v_mul_f32_e32 v153, v152, v137
	v_fma_f32 v154, -v135, v153, v152
	v_fmac_f32_e32 v153, v154, v137
	v_fma_f32 v135, -v135, v153, v152
	v_div_fmas_f32 v135, v135, v137, v153
	v_div_fixup_f32 v156, v135, v3, 1.0
	v_pk_mul_f32 v[154:155], v[100:101], v[156:157] op_sel_hi:[1,0]
	v_pk_mul_f32 v[152:153], v[98:99], v[156:157] op_sel_hi:[1,0]
	flat_store_dwordx4 v[148:149], v[152:155]
	v_ashrrev_i32_e32 v3, 31, v2
	s_nop 0
	v_pk_mul_f32 v[154:155], v[96:97], v[156:157] op_sel_hi:[1,0]
	v_pk_mul_f32 v[152:153], v[94:95], v[156:157] op_sel_hi:[1,0]
	flat_store_dwordx4 v[148:149], v[152:155] offset:16
	s_nop 1
	v_pk_mul_f32 v[154:155], v[92:93], v[156:157] op_sel_hi:[1,0]
	v_pk_mul_f32 v[152:153], v[90:91], v[156:157] op_sel_hi:[1,0]
	flat_store_dwordx4 v[148:149], v[152:155] offset:512
	s_nop 1
	v_pk_mul_f32 v[154:155], v[88:89], v[156:157] op_sel_hi:[1,0]
	v_pk_mul_f32 v[152:153], v[86:87], v[156:157] op_sel_hi:[1,0]
	flat_store_dwordx4 v[148:149], v[152:155] offset:528
	v_lshl_add_u64 v[148:149], v[2:3], 4, s[8:9]
	v_lshl_add_u64 v[148:149], v[148:149], 0, s[86:87]
	v_mov_b32_e32 v0, v245
	v_fmaak_f32 v0, v151, v0, 0x358637bd
	v_cmp_gt_f32_e32 vcc, s69, v0
	v_mul_f32_e32 v3, 0x4f800000, v0
	s_nop 0
	v_cndmask_b32_e32 v0, v0, v3, vcc
	v_sqrt_f32_e32 v3, v0
	s_nop 0
	v_add_u32_e32 v135, -1, v3
	v_fma_f32 v137, -v135, v3, v0
	v_cmp_ge_f32_e64 s[0:1], 0, v137
	v_add_u32_e32 v137, 1, v3
	s_nop 0
	v_cndmask_b32_e64 v135, v3, v135, s[0:1]
	v_fma_f32 v3, -v137, v3, v0
	v_cmp_lt_f32_e64 s[0:1], 0, v3
	s_nop 1
	v_cndmask_b32_e64 v3, v135, v137, s[0:1]
	v_mul_f32_e32 v135, 0x37800000, v3
	v_cndmask_b32_e32 v3, v3, v135, vcc
	v_cmp_class_f32_e32 vcc, v0, v217
	s_nop 1
	v_cndmask_b32_e32 v0, v3, v0, vcc
	v_div_scale_f32 v3, s[0:1], v0, v0, 1.0
	v_rcp_f32_e32 v135, v3
	s_mov_b64 s[0:1], 0x80000
	v_fma_f32 v137, -v3, v135, 1.0
	v_fmac_f32_e32 v135, v137, v135
	v_div_scale_f32 v137, vcc, 1.0, v0, 1.0
	v_mul_f32_e32 v148, v137, v135
	v_fma_f32 v149, -v3, v148, v137
	v_fmac_f32_e32 v148, v149, v135
	v_fma_f32 v3, -v3, v148, v137
	v_div_fmas_f32 v3, v3, v135, v148
	v_div_fixup_f32 v0, v3, v0, 1.0
	v_pk_mul_f32 v[154:155], v[84:85], v[0:1] op_sel_hi:[1,0]
	v_pk_mul_f32 v[152:153], v[82:83], v[0:1] op_sel_hi:[1,0]
	flat_store_dwordx4 v[142:143], v[152:155]
	s_nop 1
	v_pk_mul_f32 v[154:155], v[80:81], v[0:1] op_sel_hi:[1,0]
	v_pk_mul_f32 v[152:153], v[78:79], v[0:1] op_sel_hi:[1,0]
	flat_store_dwordx4 v[142:143], v[152:155] offset:16
	s_nop 1
	v_pk_mul_f32 v[154:155], v[76:77], v[0:1] op_sel_hi:[1,0]
	v_pk_mul_f32 v[152:153], v[74:75], v[0:1] op_sel_hi:[1,0]
	flat_store_dwordx4 v[142:143], v[152:155] offset:512
	s_nop 1
	v_pk_mul_f32 v[154:155], v[72:73], v[0:1] op_sel_hi:[1,0]
	v_pk_mul_f32 v[152:153], v[70:71], v[0:1] op_sel_hi:[1,0]
	flat_store_dwordx4 v[142:143], v[152:155] offset:528
	v_mov_b32_e32 v0, v246
	v_lshl_add_u64 v[142:143], v[138:139], 0, s[0:1]
	v_fmaak_f32 v0, v151, v0, 0x358637bd
	v_cmp_gt_f32_e32 vcc, s69, v0
	v_mul_f32_e32 v3, 0x4f800000, v0
	s_nop 0
	v_cndmask_b32_e32 v0, v0, v3, vcc
	v_sqrt_f32_e32 v3, v0
	s_nop 0
	v_add_u32_e32 v135, -1, v3
	v_fma_f32 v137, -v135, v3, v0
	v_cmp_ge_f32_e64 s[0:1], 0, v137
	v_add_u32_e32 v137, 1, v3
	s_nop 0
	v_cndmask_b32_e64 v135, v3, v135, s[0:1]
	v_fma_f32 v3, -v137, v3, v0
	v_cmp_lt_f32_e64 s[0:1], 0, v3
	s_nop 1
	v_cndmask_b32_e64 v3, v135, v137, s[0:1]
	v_mul_f32_e32 v135, 0x37800000, v3
	v_cndmask_b32_e32 v3, v3, v135, vcc
	v_cmp_class_f32_e32 vcc, v0, v217
	s_nop 1
	v_cndmask_b32_e32 v0, v3, v0, vcc
	v_div_scale_f32 v3, s[0:1], v0, v0, 1.0
	v_rcp_f32_e32 v135, v3
	s_mov_b32 s0, 0x80000
	v_fma_f32 v137, -v3, v135, 1.0
	v_fmac_f32_e32 v135, v137, v135
	v_div_scale_f32 v137, vcc, 1.0, v0, 1.0
	v_mul_f32_e32 v148, v137, v135
	v_fma_f32 v149, -v3, v148, v137
	v_fmac_f32_e32 v148, v149, v135
	v_fma_f32 v3, -v3, v148, v137
	v_div_fmas_f32 v3, v3, v135, v148
	v_div_fixup_f32 v0, v3, v0, 1.0
	v_add_co_u32_e32 v148, vcc, s0, v138
	v_pk_mul_f32 v[154:155], v[68:69], v[0:1] op_sel_hi:[1,0]
	v_pk_mul_f32 v[152:153], v[66:67], v[0:1] op_sel_hi:[1,0]
	v_addc_co_u32_e32 v149, vcc, 0, v139, vcc
	flat_store_dwordx4 v[148:149], v[152:155]
	s_mov_b64 s[0:1], 0x90000
	s_nop 0
	v_pk_mul_f32 v[154:155], v[64:65], v[0:1] op_sel_hi:[1,0]
	v_pk_mul_f32 v[152:153], v[62:63], v[0:1] op_sel_hi:[1,0]
	flat_store_dwordx4 v[142:143], v[152:155] offset:16
	s_nop 1
	v_pk_mul_f32 v[154:155], v[60:61], v[0:1] op_sel_hi:[1,0]
	v_pk_mul_f32 v[152:153], v[58:59], v[0:1] op_sel_hi:[1,0]
	flat_store_dwordx4 v[142:143], v[152:155] offset:512
	s_nop 1
	v_pk_mul_f32 v[154:155], v[56:57], v[0:1] op_sel_hi:[1,0]
	v_pk_mul_f32 v[152:153], v[54:55], v[0:1] op_sel_hi:[1,0]
	flat_store_dwordx4 v[142:143], v[152:155] offset:528
	v_mov_b32_e32 v0, v247
;     __device__ __forceinline__ void operator()(const f32x4 (&acc)[2][2][4][2], const Unit& u, int wr, int wc, int fr, int fq) const {
;     ...
;                 for (int m = 0; m < 4; ++m) { const int row = row0 + ai * HALF + m * 16; float* yp = y32 + ((size_t)slice * 512 + crow0 + ai * HALF + m * 16) * DM + col0;
;                     float sc = 1.0f; if (SEG) sc = 1.0f / sqrtf(ss[(size_t)row * 4 + seg] * nn + LN_EPS);
; #pragma unroll
;                     for (int bj = 0; bj < 2; ++bj)
; #pragma unroll
;                         for (int n = 0; n < 2; ++n) *(f32x4*)(yp + bj * HALF + 4 * n) = acc[ai][bj][m][n] * sc; }
	v_lshl_add_u64 v[142:143], v[138:139], 0, s[0:1]
	v_fmaak_f32 v0, v151, v0, 0x358637bd
	v_cmp_gt_f32_e32 vcc, s69, v0
	v_mul_f32_e32 v3, 0x4f800000, v0
	s_nop 0
	v_cndmask_b32_e32 v0, v0, v3, vcc
	v_sqrt_f32_e32 v3, v0
	s_nop 0
	v_add_u32_e32 v135, -1, v3
	v_fma_f32 v137, -v135, v3, v0
	v_cmp_ge_f32_e64 s[0:1], 0, v137
	v_add_u32_e32 v137, 1, v3
	s_nop 0
	v_cndmask_b32_e64 v135, v3, v135, s[0:1]
	v_fma_f32 v3, -v137, v3, v0
	v_cmp_lt_f32_e64 s[0:1], 0, v3
	s_nop 1
	v_cndmask_b32_e64 v3, v135, v137, s[0:1]
	v_mul_f32_e32 v135, 0x37800000, v3
	v_cndmask_b32_e32 v3, v3, v135, vcc
	v_cmp_class_f32_e32 vcc, v0, v217
	s_nop 1
	v_cndmask_b32_e32 v0, v3, v0, vcc
	v_div_scale_f32 v3, s[0:1], v0, v0, 1.0
	v_rcp_f32_e32 v135, v3
	s_mov_b32 s0, 0x90000
	v_fma_f32 v137, -v3, v135, 1.0
	v_fmac_f32_e32 v135, v137, v135
	v_div_scale_f32 v137, vcc, 1.0, v0, 1.0
	v_mul_f32_e32 v148, v137, v135
	v_fma_f32 v149, -v3, v148, v137
	v_fmac_f32_e32 v148, v149, v135
	v_fma_f32 v3, -v3, v148, v137
	v_div_fmas_f32 v3, v3, v135, v148
	v_div_fixup_f32 v0, v3, v0, 1.0
	v_add_co_u32_e32 v148, vcc, s0, v138
	v_pk_mul_f32 v[154:155], v[52:53], v[0:1] op_sel_hi:[1,0]
	v_pk_mul_f32 v[152:153], v[50:51], v[0:1] op_sel_hi:[1,0]
	v_addc_co_u32_e32 v149, vcc, 0, v139, vcc
	flat_store_dwordx4 v[148:149], v[152:155]
	s_mov_b64 s[0:1], 0xa0000
	s_nop 0
	v_pk_mul_f32 v[154:155], v[48:49], v[0:1] op_sel_hi:[1,0]
	v_pk_mul_f32 v[152:153], v[46:47], v[0:1] op_sel_hi:[1,0]
	flat_store_dwordx4 v[142:143], v[152:155] offset:16
	s_nop 1
	v_pk_mul_f32 v[154:155], v[44:45], v[0:1] op_sel_hi:[1,0]
	v_pk_mul_f32 v[152:153], v[42:43], v[0:1] op_sel_hi:[1,0]
	flat_store_dwordx4 v[142:143], v[152:155] offset:512
	s_nop 1
	v_pk_mul_f32 v[154:155], v[40:41], v[0:1] op_sel_hi:[1,0]
	v_pk_mul_f32 v[152:153], v[38:39], v[0:1] op_sel_hi:[1,0]
	flat_store_dwordx4 v[142:143], v[152:155] offset:528
	v_mov_b32_e32 v0, v248
	v_lshl_add_u64 v[142:143], v[138:139], 0, s[0:1]
	v_fmaak_f32 v0, v151, v0, 0x358637bd
	v_cmp_gt_f32_e32 vcc, s69, v0
	v_mul_f32_e32 v3, 0x4f800000, v0
	s_nop 0
	v_cndmask_b32_e32 v0, v0, v3, vcc
	v_sqrt_f32_e32 v3, v0
	s_nop 0
	v_add_u32_e32 v135, -1, v3
	v_fma_f32 v137, -v135, v3, v0
	v_cmp_ge_f32_e64 s[0:1], 0, v137
	v_add_u32_e32 v137, 1, v3
	s_nop 0
	v_cndmask_b32_e64 v135, v3, v135, s[0:1]
	v_fma_f32 v3, -v137, v3, v0
	v_cmp_lt_f32_e64 s[0:1], 0, v3
	s_nop 1
	v_cndmask_b32_e64 v3, v135, v137, s[0:1]
	v_mul_f32_e32 v135, 0x37800000, v3
	v_cndmask_b32_e32 v3, v3, v135, vcc
	v_cmp_class_f32_e32 vcc, v0, v217
	s_nop 1
	v_cndmask_b32_e32 v0, v3, v0, vcc
	v_div_scale_f32 v3, s[0:1], v0, v0, 1.0
	v_rcp_f32_e32 v135, v3
	s_mov_b32 s0, 0xa0000
	v_fma_f32 v137, -v3, v135, 1.0
	v_fmac_f32_e32 v135, v137, v135
	v_div_scale_f32 v137, vcc, 1.0, v0, 1.0
	v_mul_f32_e32 v148, v137, v135
	v_fma_f32 v149, -v3, v148, v137
	v_fmac_f32_e32 v148, v149, v135
	v_fma_f32 v3, -v3, v148, v137
	v_div_fmas_f32 v3, v3, v135, v148
	v_div_fixup_f32 v0, v3, v0, 1.0
	v_add_co_u32_e32 v148, vcc, s0, v138
	v_pk_mul_f32 v[154:155], v[36:37], v[0:1] op_sel_hi:[1,0]
	v_pk_mul_f32 v[152:153], v[34:35], v[0:1] op_sel_hi:[1,0]
	v_addc_co_u32_e32 v149, vcc, 0, v139, vcc
	flat_store_dwordx4 v[148:149], v[152:155]
	s_mov_b64 s[0:1], 0xb0000
	s_nop 0
	v_pk_mul_f32 v[154:155], v[32:33], v[0:1] op_sel_hi:[1,0]
	v_pk_mul_f32 v[152:153], v[30:31], v[0:1] op_sel_hi:[1,0]
	flat_store_dwordx4 v[142:143], v[152:155] offset:16
	s_nop 1
	v_pk_mul_f32 v[154:155], v[28:29], v[0:1] op_sel_hi:[1,0]
	v_pk_mul_f32 v[152:153], v[26:27], v[0:1] op_sel_hi:[1,0]
	flat_store_dwordx4 v[142:143], v[152:155] offset:512
	s_nop 1
	v_pk_mul_f32 v[154:155], v[24:25], v[0:1] op_sel_hi:[1,0]
	v_pk_mul_f32 v[152:153], v[22:23], v[0:1] op_sel_hi:[1,0]
	flat_store_dwordx4 v[142:143], v[152:155] offset:528
	v_mov_b32_e32 v0, v249
	v_lshl_add_u64 v[142:143], v[138:139], 0, s[0:1]
	v_fmaak_f32 v0, v151, v0, 0x358637bd
	v_cmp_gt_f32_e32 vcc, s69, v0
	v_mul_f32_e32 v3, 0x4f800000, v0
	s_nop 0
	v_cndmask_b32_e32 v0, v0, v3, vcc
	v_sqrt_f32_e32 v3, v0
	s_nop 0
	v_add_u32_e32 v135, -1, v3
	v_fma_f32 v137, -v135, v3, v0
	v_cmp_ge_f32_e64 s[0:1], 0, v137
	v_add_u32_e32 v137, 1, v3
	s_nop 0
	v_cndmask_b32_e64 v135, v3, v135, s[0:1]
	v_fma_f32 v3, -v137, v3, v0
	v_cmp_lt_f32_e64 s[0:1], 0, v3
	s_nop 1
	v_cndmask_b32_e64 v3, v135, v137, s[0:1]
	v_mul_f32_e32 v135, 0x37800000, v3
	v_cndmask_b32_e32 v3, v3, v135, vcc
	v_cmp_class_f32_e32 vcc, v0, v217
	s_nop 1
	v_cndmask_b32_e32 v0, v3, v0, vcc
	v_div_scale_f32 v3, s[0:1], v0, v0, 1.0
	v_rcp_f32_e32 v135, v3
	s_mov_b32 s0, 0xb0000
	v_fma_f32 v137, -v3, v135, 1.0
	v_fmac_f32_e32 v135, v137, v135
	v_div_scale_f32 v137, vcc, 1.0, v0, 1.0
	v_mul_f32_e32 v140, v137, v135
	v_fma_f32 v141, -v3, v140, v137
	v_fmac_f32_e32 v140, v141, v135
	v_fma_f32 v3, -v3, v140, v137
	v_div_fmas_f32 v3, v3, v135, v140
	v_div_fixup_f32 v0, v3, v0, 1.0
	v_add_co_u32_e32 v138, vcc, s0, v138
	v_pk_mul_f32 v[154:155], v[20:21], v[0:1] op_sel_hi:[1,0]
	v_pk_mul_f32 v[152:153], v[18:19], v[0:1] op_sel_hi:[1,0]
	v_addc_co_u32_e32 v139, vcc, 0, v139, vcc
	flat_store_dwordx4 v[138:139], v[152:155]
	v_pk_mul_f32 v[140:141], v[14:15], v[0:1] op_sel_hi:[1,0]
	v_pk_mul_f32 v[138:139], v[12:13], v[0:1] op_sel_hi:[1,0]
	flat_store_dwordx4 v[142:143], v[138:141] offset:16
	s_mov_b64 s[0:1], 0
	s_nop 0
	v_pk_mul_f32 v[140:141], v[10:11], v[0:1] op_sel_hi:[1,0]
	v_pk_mul_f32 v[138:139], v[8:9], v[0:1] op_sel_hi:[1,0]
	flat_store_dwordx4 v[142:143], v[138:141] offset:512
	s_nop 1
	v_pk_mul_f32 v[140:141], v[6:7], v[0:1] op_sel_hi:[1,0]
	v_pk_mul_f32 v[138:139], v[4:5], v[0:1] op_sel_hi:[1,0]
	flat_store_dwordx4 v[142:143], v[138:141] offset:528
